# P6 tmp (gate_sb*u_sb partial, bf16) kept in the dead ST region of d_ws instead of d_out
# speedup vs baseline: 1.0002x; 1.0002x over previous
; __device__ __forceinline__ unsigned cvt_pk_bf16(float lo, float hi) { f32x2_t v = {lo, hi}; bf16x2_t b = __builtin_convertvector(v, bf16x2_t); return __builtin_bit_cast(unsigned, b); }
; __device__ __forceinline__ float bf2f(unsigned u) { return __uint_as_float(u << 16); }
;     __device__ __forceinline__ void operator()(const f32x4 (&acc)[2][2][4][2], const pg8::Unit& u, int wr, int wc, int fr, int fq) const {
;         const bool second = u.pm >= 64;
;         const int pm = second ? u.pm - 64 : u.pm, pn = second ? u.pn - 4 : u.pn;
;         const int row0 = pm * 256 + wr * 64 + fr, col0 = pn * 256 + wc * 32 + 8 * fq;
; #pragma unroll
;         for (int ai = 0; ai < 2; ++ai)
; #pragma unroll
;         for (int mh = 0; mh < 2; ++mh) {
;             u32x4 gv[2][2], tv[2][2];
; #pragma unroll
;             for (int mm = 0; mm < 2; ++mm)
; #pragma unroll
;                 for (int bj = 0; bj < 2; ++bj) {
;                     const size_t row = (size_t)(row0 + ai * 128 + (2 * mh + mm) * 16); const int col = col0 + bj * 128;
;                     gv[mm][bj] = *(const u32x4*)(gates + row * 2048 + (second ? 1024 : 0) + col);
;                     if (second) tv[mm][bj] = *(const u32x4*)((const bf16_t*)tmp + row * 1024 + col);
;                 }
; #pragma unroll
;             for (int mm = 0; mm < 2; ++mm)
; #pragma unroll
;                 for (int bj = 0; bj < 2; ++bj) {
;                     const int m = 2 * mh + mm;
;                     const size_t row = (size_t)(row0 + ai * 128 + m * 16); const int col = col0 + bj * 128;
;                     const u32x4 gt = gv[mm][bj];
;                     f32x4 a = acc[ai][bj][m][0], b = acc[ai][bj][m][1];
;                     a[0] *= bf2f(gt.x & 0xffffu); a[1] *= bf2f(gt.x >> 16); a[2] *= bf2f(gt.y & 0xffffu); a[3] *= bf2f(gt.y >> 16);
;                     b[0] *= bf2f(gt.z & 0xffffu); b[1] *= bf2f(gt.z >> 16); b[2] *= bf2f(gt.w & 0xffffu); b[3] *= bf2f(gt.w >> 16);
;                     if (!second) { u32x4 w; w.x = cvt_pk_bf16(a[0], a[1]); w.y = cvt_pk_bf16(a[2], a[3]); w.z = cvt_pk_bf16(b[0], b[1]); w.w = cvt_pk_bf16(b[2], b[3]); *(u32x4*)((bf16_t*)tmp + row * 1024 + col) = w; }
.LBB0_612:
	s_add_u32 s98, s66, 0xdc00000
	s_addc_u32 s99, s67, 0
	s_lshl_b32 s3, s4, 8
	s_lshl_b32 s17, s24, 8
	s_add_i32 s5, s3, 0xffffc000
	s_add_i32 s19, s17, 0xfffffc00
	s_cmp_gt_i32 s4, 63
	s_cselect_b64 s[26:27], -1, 0
	s_cselect_b32 s3, s5, s3
	s_cselect_b32 s5, s19, s17
	s_cselect_b32 s17, 0x800, 0
	s_add_u32 s24, s72, s17
	s_addc_u32 s25, s73, 0
	s_mov_b32 s19, 0xffff0000
	v_add_u32_e32 v178, s3, v186
	v_or_b32_e32 v176, s5, v188
	v_lshlrev_b32_e32 v177, 1, v176
	v_lshl_add_u32 v180, v178, 12, v177
	v_lshl_add_u32 v181, v178, 11, v177
	global_load_dwordx4 v[72:75], v180, s[24:25]
	global_load_dwordx4 v[84:87], v180, s[24:25] offset:256
	v_add_u32_e32 v176, 0x10000, v180
	global_load_dwordx4 v[96:99], v176, s[24:25]
	global_load_dwordx4 v[100:103], v176, s[24:25] offset:256
	v_add_u32_e32 v177, 0x20000, v180
	global_load_dwordx4 v[144:147], v177, s[24:25]
	global_load_dwordx4 v[148:151], v177, s[24:25] offset:256
	v_add_u32_e32 v178, 0x30000, v180
	global_load_dwordx4 v[152:155], v178, s[24:25]
	global_load_dwordx4 v[156:159], v178, s[24:25] offset:256
	v_add_u32_e32 v179, 0x80000, v180
	global_load_dwordx4 v[192:195], v179, s[24:25]
	global_load_dwordx4 v[196:199], v179, s[24:25] offset:256
	v_add_u32_e32 v176, 0x90000, v180
	global_load_dwordx4 v[202:205], v176, s[24:25]
	global_load_dwordx4 v[206:209], v176, s[24:25] offset:256
	v_add_u32_e32 v177, 0xa0000, v180
	global_load_dwordx4 v[210:213], v177, s[24:25]
	global_load_dwordx4 v[214:217], v177, s[24:25] offset:256
	v_add_u32_e32 v178, 0xb0000, v180
	global_load_dwordx4 v[218:221], v178, s[24:25]
	global_load_dwordx4 v[222:225], v178, s[24:25] offset:256
	s_and_b64 vcc, exec, s[26:27]
	s_cbranch_vccnz .Lepic_second
	v_readfirstlane_b32 s3, v200
	s_nop 0
	s_lshr_b32 s3, s3, 6
	s_cmp_eq_u32 s3, 0
	s_cbranch_scc1 .Ldry_epicf_real
	s_mov_b64 exec, 0
	s_cmp_eq_u32 s3, 1
	s_cbranch_scc1 .Ldry_epicf_c1
	s_cmp_eq_u32 s3, 2
	s_cbranch_scc1 .Ldry_epicf_c2
	s_cmp_eq_u32 s3, 3
	s_cbranch_scc1 .Ldry_epicf_c3
	s_cmp_eq_u32 s3, 4
	s_cbranch_scc1 .Ldry_epicf_c4
	s_cmp_eq_u32 s3, 5
	s_cbranch_scc1 .Ldry_epicf_c5
	s_cmp_eq_u32 s3, 6
	s_cbranch_scc1 .Ldry_epicf_c6
	s_branch .Ldry_epicf_c7
.Ldry_epicf_real:
	s_mov_b64 exec, -1
	s_waitcnt vmcnt(15)
	v_lshlrev_b32_e32 v176, 16, v72
	v_and_b32_e32 v177, s19, v72
	v_lshlrev_b32_e32 v178, 16, v73
	v_and_b32_e32 v179, s19, v73
	v_lshlrev_b32_e32 v182, 16, v74
	v_and_b32_e32 v183, s19, v74
	v_lshlrev_b32_e32 v184, 16, v75
	v_and_b32_e32 v185, s19, v75
	v_pk_mul_f32 v[140:141], v[140:141], v[176:177]
	v_pk_mul_f32 v[142:143], v[142:143], v[178:179]
	v_pk_mul_f32 v[136:137], v[136:137], v[182:183]
	v_pk_mul_f32 v[138:139], v[138:139], v[184:185]
	v_cvt_pk_bf16_f32 v140, v140, v141
	v_cvt_pk_bf16_f32 v141, v142, v143
	v_cvt_pk_bf16_f32 v142, v136, v137
	v_cvt_pk_bf16_f32 v143, v138, v139
	v_mov_b32_e32 v180, v181
	global_store_dwordx4 v180, v[140:143], s[98:99]
	s_waitcnt vmcnt(15)
	v_lshlrev_b32_e32 v176, 16, v84
	v_and_b32_e32 v177, s19, v84
	v_lshlrev_b32_e32 v178, 16, v85
	v_and_b32_e32 v179, s19, v85
	v_lshlrev_b32_e32 v182, 16, v86
	v_and_b32_e32 v183, s19, v86
	v_lshlrev_b32_e32 v184, 16, v87
	v_and_b32_e32 v185, s19, v87
	v_pk_mul_f32 v[132:133], v[132:133], v[176:177]
	v_pk_mul_f32 v[134:135], v[134:135], v[178:179]
	v_pk_mul_f32 v[128:129], v[128:129], v[182:183]
	v_pk_mul_f32 v[130:131], v[130:131], v[184:185]
	v_cvt_pk_bf16_f32 v132, v132, v133
	v_cvt_pk_bf16_f32 v133, v134, v135
	v_cvt_pk_bf16_f32 v134, v128, v129
	v_cvt_pk_bf16_f32 v135, v130, v131
	global_store_dwordx4 v180, v[132:135], s[98:99] offset:256
	s_cbranch_execz .Ldry_epicf_real
.Ldry_epicf_c1:
	s_waitcnt vmcnt(15)
	v_lshlrev_b32_e32 v176, 16, v96
	v_and_b32_e32 v177, s19, v96
	v_lshlrev_b32_e32 v178, 16, v97
	v_and_b32_e32 v179, s19, v97
	v_lshlrev_b32_e32 v182, 16, v98
	v_and_b32_e32 v183, s19, v98
	v_lshlrev_b32_e32 v184, 16, v99
	v_and_b32_e32 v185, s19, v99
	v_pk_mul_f32 v[124:125], v[124:125], v[176:177]
	v_pk_mul_f32 v[126:127], v[126:127], v[178:179]
	v_pk_mul_f32 v[120:121], v[120:121], v[182:183]
	v_pk_mul_f32 v[122:123], v[122:123], v[184:185]
	v_cvt_pk_bf16_f32 v124, v124, v125
	v_cvt_pk_bf16_f32 v125, v126, v127
	v_cvt_pk_bf16_f32 v126, v120, v121
	v_cvt_pk_bf16_f32 v127, v122, v123
	v_add_u32_e32 v180, 0x8000, v181
	global_store_dwordx4 v180, v[124:127], s[98:99]
	s_waitcnt vmcnt(15)
	v_lshlrev_b32_e32 v176, 16, v100
	v_and_b32_e32 v177, s19, v100
	v_lshlrev_b32_e32 v178, 16, v101
	v_and_b32_e32 v179, s19, v101
	v_lshlrev_b32_e32 v182, 16, v102
	v_and_b32_e32 v183, s19, v102
	v_lshlrev_b32_e32 v184, 16, v103
	v_and_b32_e32 v185, s19, v103
	v_pk_mul_f32 v[116:117], v[116:117], v[176:177]
	v_pk_mul_f32 v[118:119], v[118:119], v[178:179]
	v_pk_mul_f32 v[112:113], v[112:113], v[182:183]
	v_pk_mul_f32 v[114:115], v[114:115], v[184:185]
	v_cvt_pk_bf16_f32 v116, v116, v117
	v_cvt_pk_bf16_f32 v117, v118, v119
	v_cvt_pk_bf16_f32 v118, v112, v113
	v_cvt_pk_bf16_f32 v119, v114, v115
	global_store_dwordx4 v180, v[116:119], s[98:99] offset:256
	s_cbranch_execz .Ldry_epicf_real
; __device__ __forceinline__ unsigned cvt_pk_bf16(float lo, float hi) { f32x2_t v = {lo, hi}; bf16x2_t b = __builtin_convertvector(v, bf16x2_t); return __builtin_bit_cast(unsigned, b); }
; __device__ __forceinline__ float bf2f(unsigned u) { return __uint_as_float(u << 16); }
;     __device__ __forceinline__ void operator()(const f32x4 (&acc)[2][2][4][2], const pg8::Unit& u, int wr, int wc, int fr, int fq) const {
;     ...
;                     const u32x4 gt = gv[mm][bj];
;                     f32x4 a = acc[ai][bj][m][0], b = acc[ai][bj][m][1];
;                     a[0] *= bf2f(gt.x & 0xffffu); a[1] *= bf2f(gt.x >> 16); a[2] *= bf2f(gt.y & 0xffffu); a[3] *= bf2f(gt.y >> 16);
;                     b[0] *= bf2f(gt.z & 0xffffu); b[1] *= bf2f(gt.z >> 16); b[2] *= bf2f(gt.w & 0xffffu); b[3] *= bf2f(gt.w >> 16);
;                     if (!second) { u32x4 w; w.x = cvt_pk_bf16(a[0], a[1]); w.y = cvt_pk_bf16(a[2], a[3]); w.z = cvt_pk_bf16(b[0], b[1]); w.w = cvt_pk_bf16(b[2], b[3]); *(u32x4*)((bf16_t*)tmp + row * 1024 + col) = w; }
.Ldry_epicf_c2:
	s_waitcnt vmcnt(15)
	v_lshlrev_b32_e32 v176, 16, v144
	v_and_b32_e32 v177, s19, v144
	v_lshlrev_b32_e32 v178, 16, v145
	v_and_b32_e32 v179, s19, v145
	v_lshlrev_b32_e32 v182, 16, v146
	v_and_b32_e32 v183, s19, v146
	v_lshlrev_b32_e32 v184, 16, v147
	v_and_b32_e32 v185, s19, v147
	v_pk_mul_f32 v[108:109], v[108:109], v[176:177]
	v_pk_mul_f32 v[110:111], v[110:111], v[178:179]
	v_pk_mul_f32 v[104:105], v[104:105], v[182:183]
	v_pk_mul_f32 v[106:107], v[106:107], v[184:185]
	v_cvt_pk_bf16_f32 v108, v108, v109
	v_cvt_pk_bf16_f32 v109, v110, v111
	v_cvt_pk_bf16_f32 v110, v104, v105
	v_cvt_pk_bf16_f32 v111, v106, v107
	v_add_u32_e32 v180, 0x10000, v181
	global_store_dwordx4 v180, v[108:111], s[98:99]
	s_waitcnt vmcnt(15)
	v_lshlrev_b32_e32 v176, 16, v148
	v_and_b32_e32 v177, s19, v148
	v_lshlrev_b32_e32 v178, 16, v149
	v_and_b32_e32 v179, s19, v149
	v_lshlrev_b32_e32 v182, 16, v150
	v_and_b32_e32 v183, s19, v150
	v_lshlrev_b32_e32 v184, 16, v151
	v_and_b32_e32 v185, s19, v151
	v_pk_mul_f32 v[92:93], v[92:93], v[176:177]
	v_pk_mul_f32 v[94:95], v[94:95], v[178:179]
	v_pk_mul_f32 v[88:89], v[88:89], v[182:183]
	v_pk_mul_f32 v[90:91], v[90:91], v[184:185]
	v_cvt_pk_bf16_f32 v92, v92, v93
	v_cvt_pk_bf16_f32 v93, v94, v95
	v_cvt_pk_bf16_f32 v94, v88, v89
	v_cvt_pk_bf16_f32 v95, v90, v91
	global_store_dwordx4 v180, v[92:95], s[98:99] offset:256
	s_cbranch_execz .Ldry_epicf_real
.Ldry_epicf_c3:
	s_waitcnt vmcnt(15)
	v_lshlrev_b32_e32 v176, 16, v152
	v_and_b32_e32 v177, s19, v152
	v_lshlrev_b32_e32 v178, 16, v153
	v_and_b32_e32 v179, s19, v153
	v_lshlrev_b32_e32 v182, 16, v154
	v_and_b32_e32 v183, s19, v154
	v_lshlrev_b32_e32 v184, 16, v155
	v_and_b32_e32 v185, s19, v155
	v_pk_mul_f32 v[80:81], v[80:81], v[176:177]
	v_pk_mul_f32 v[82:83], v[82:83], v[178:179]
	v_pk_mul_f32 v[76:77], v[76:77], v[182:183]
	v_pk_mul_f32 v[78:79], v[78:79], v[184:185]
	v_cvt_pk_bf16_f32 v80, v80, v81
	v_cvt_pk_bf16_f32 v81, v82, v83
	v_cvt_pk_bf16_f32 v82, v76, v77
	v_cvt_pk_bf16_f32 v83, v78, v79
	v_add_u32_e32 v180, 0x18000, v181
	global_store_dwordx4 v180, v[80:83], s[98:99]
	s_waitcnt vmcnt(15)
	v_lshlrev_b32_e32 v176, 16, v156
	v_and_b32_e32 v177, s19, v156
	v_lshlrev_b32_e32 v178, 16, v157
	v_and_b32_e32 v179, s19, v157
	v_lshlrev_b32_e32 v182, 16, v158
	v_and_b32_e32 v183, s19, v158
	v_lshlrev_b32_e32 v184, 16, v159
	v_and_b32_e32 v185, s19, v159
	v_pk_mul_f32 v[68:69], v[68:69], v[176:177]
	v_pk_mul_f32 v[70:71], v[70:71], v[178:179]
	v_pk_mul_f32 v[64:65], v[64:65], v[182:183]
	v_pk_mul_f32 v[66:67], v[66:67], v[184:185]
	v_cvt_pk_bf16_f32 v68, v68, v69
	v_cvt_pk_bf16_f32 v69, v70, v71
	v_cvt_pk_bf16_f32 v70, v64, v65
	v_cvt_pk_bf16_f32 v71, v66, v67
	global_store_dwordx4 v180, v[68:71], s[98:99] offset:256
	s_cbranch_execz .Ldry_epicf_real
.Ldry_epicf_c4:
	s_waitcnt vmcnt(15)
	v_lshlrev_b32_e32 v176, 16, v192
	v_and_b32_e32 v177, s19, v192
	v_lshlrev_b32_e32 v178, 16, v193
	v_and_b32_e32 v179, s19, v193
	v_lshlrev_b32_e32 v182, 16, v194
	v_and_b32_e32 v183, s19, v194
	v_lshlrev_b32_e32 v184, 16, v195
	v_and_b32_e32 v185, s19, v195
	v_pk_mul_f32 v[60:61], v[60:61], v[176:177]
	v_pk_mul_f32 v[62:63], v[62:63], v[178:179]
	v_pk_mul_f32 v[56:57], v[56:57], v[182:183]
	v_pk_mul_f32 v[58:59], v[58:59], v[184:185]
	v_cvt_pk_bf16_f32 v60, v60, v61
	v_cvt_pk_bf16_f32 v61, v62, v63
	v_cvt_pk_bf16_f32 v62, v56, v57
	v_cvt_pk_bf16_f32 v63, v58, v59
	v_add_u32_e32 v180, 0x40000, v181
	global_store_dwordx4 v180, v[60:63], s[98:99]
	s_waitcnt vmcnt(15)
	v_lshlrev_b32_e32 v176, 16, v196
	v_and_b32_e32 v177, s19, v196
	v_lshlrev_b32_e32 v178, 16, v197
	v_and_b32_e32 v179, s19, v197
	v_lshlrev_b32_e32 v182, 16, v198
	v_and_b32_e32 v183, s19, v198
	v_lshlrev_b32_e32 v184, 16, v199
	v_and_b32_e32 v185, s19, v199
	v_pk_mul_f32 v[52:53], v[52:53], v[176:177]
	v_pk_mul_f32 v[54:55], v[54:55], v[178:179]
	v_pk_mul_f32 v[48:49], v[48:49], v[182:183]
	v_pk_mul_f32 v[50:51], v[50:51], v[184:185]
	v_cvt_pk_bf16_f32 v52, v52, v53
	v_cvt_pk_bf16_f32 v53, v54, v55
	v_cvt_pk_bf16_f32 v54, v48, v49
	v_cvt_pk_bf16_f32 v55, v50, v51
	global_store_dwordx4 v180, v[52:55], s[98:99] offset:256
	s_cbranch_execz .Ldry_epicf_real
; __device__ __forceinline__ unsigned cvt_pk_bf16(float lo, float hi) { f32x2_t v = {lo, hi}; bf16x2_t b = __builtin_convertvector(v, bf16x2_t); return __builtin_bit_cast(unsigned, b); }
; __device__ __forceinline__ float bf2f(unsigned u) { return __uint_as_float(u << 16); }
;     __device__ __forceinline__ void operator()(const f32x4 (&acc)[2][2][4][2], const pg8::Unit& u, int wr, int wc, int fr, int fq) const {
;     ...
;                     const u32x4 gt = gv[mm][bj];
;                     f32x4 a = acc[ai][bj][m][0], b = acc[ai][bj][m][1];
;                     a[0] *= bf2f(gt.x & 0xffffu); a[1] *= bf2f(gt.x >> 16); a[2] *= bf2f(gt.y & 0xffffu); a[3] *= bf2f(gt.y >> 16);
;                     b[0] *= bf2f(gt.z & 0xffffu); b[1] *= bf2f(gt.z >> 16); b[2] *= bf2f(gt.w & 0xffffu); b[3] *= bf2f(gt.w >> 16);
;                     if (!second) { u32x4 w; w.x = cvt_pk_bf16(a[0], a[1]); w.y = cvt_pk_bf16(a[2], a[3]); w.z = cvt_pk_bf16(b[0], b[1]); w.w = cvt_pk_bf16(b[2], b[3]); *(u32x4*)((bf16_t*)tmp + row * 1024 + col) = w; }
.Ldry_epicf_c5:
	s_waitcnt vmcnt(15)
	v_lshlrev_b32_e32 v176, 16, v202
	v_and_b32_e32 v177, s19, v202
	v_lshlrev_b32_e32 v178, 16, v203
	v_and_b32_e32 v179, s19, v203
	v_lshlrev_b32_e32 v182, 16, v204
	v_and_b32_e32 v183, s19, v204
	v_lshlrev_b32_e32 v184, 16, v205
	v_and_b32_e32 v185, s19, v205
	v_pk_mul_f32 v[44:45], v[44:45], v[176:177]
	v_pk_mul_f32 v[46:47], v[46:47], v[178:179]
	v_pk_mul_f32 v[40:41], v[40:41], v[182:183]
	v_pk_mul_f32 v[42:43], v[42:43], v[184:185]
	v_cvt_pk_bf16_f32 v44, v44, v45
	v_cvt_pk_bf16_f32 v45, v46, v47
	v_cvt_pk_bf16_f32 v46, v40, v41
	v_cvt_pk_bf16_f32 v47, v42, v43
	v_add_u32_e32 v180, 0x48000, v181
	global_store_dwordx4 v180, v[44:47], s[98:99]
	s_waitcnt vmcnt(15)
	v_lshlrev_b32_e32 v176, 16, v206
	v_and_b32_e32 v177, s19, v206
	v_lshlrev_b32_e32 v178, 16, v207
	v_and_b32_e32 v179, s19, v207
	v_lshlrev_b32_e32 v182, 16, v208
	v_and_b32_e32 v183, s19, v208
	v_lshlrev_b32_e32 v184, 16, v209
	v_and_b32_e32 v185, s19, v209
	v_pk_mul_f32 v[36:37], v[36:37], v[176:177]
	v_pk_mul_f32 v[38:39], v[38:39], v[178:179]
	v_pk_mul_f32 v[32:33], v[32:33], v[182:183]
	v_pk_mul_f32 v[34:35], v[34:35], v[184:185]
	v_cvt_pk_bf16_f32 v36, v36, v37
	v_cvt_pk_bf16_f32 v37, v38, v39
	v_cvt_pk_bf16_f32 v38, v32, v33
	v_cvt_pk_bf16_f32 v39, v34, v35
	global_store_dwordx4 v180, v[36:39], s[98:99] offset:256
	s_cbranch_execz .Ldry_epicf_real
.Ldry_epicf_c6:
	s_waitcnt vmcnt(15)
	v_lshlrev_b32_e32 v176, 16, v210
	v_and_b32_e32 v177, s19, v210
	v_lshlrev_b32_e32 v178, 16, v211
	v_and_b32_e32 v179, s19, v211
	v_lshlrev_b32_e32 v182, 16, v212
	v_and_b32_e32 v183, s19, v212
	v_lshlrev_b32_e32 v184, 16, v213
	v_and_b32_e32 v185, s19, v213
	v_pk_mul_f32 v[28:29], v[28:29], v[176:177]
	v_pk_mul_f32 v[30:31], v[30:31], v[178:179]
	v_pk_mul_f32 v[24:25], v[24:25], v[182:183]
	v_pk_mul_f32 v[26:27], v[26:27], v[184:185]
	v_cvt_pk_bf16_f32 v28, v28, v29
	v_cvt_pk_bf16_f32 v29, v30, v31
	v_cvt_pk_bf16_f32 v30, v24, v25
	v_cvt_pk_bf16_f32 v31, v26, v27
	v_add_u32_e32 v180, 0x50000, v181
	global_store_dwordx4 v180, v[28:31], s[98:99]
	s_waitcnt vmcnt(15)
	v_lshlrev_b32_e32 v176, 16, v214
	v_and_b32_e32 v177, s19, v214
	v_lshlrev_b32_e32 v178, 16, v215
	v_and_b32_e32 v179, s19, v215
	v_lshlrev_b32_e32 v182, 16, v216
	v_and_b32_e32 v183, s19, v216
	v_lshlrev_b32_e32 v184, 16, v217
	v_and_b32_e32 v185, s19, v217
	v_pk_mul_f32 v[20:21], v[20:21], v[176:177]
	v_pk_mul_f32 v[22:23], v[22:23], v[178:179]
	v_pk_mul_f32 v[16:17], v[16:17], v[182:183]
	v_pk_mul_f32 v[18:19], v[18:19], v[184:185]
	v_cvt_pk_bf16_f32 v20, v20, v21
	v_cvt_pk_bf16_f32 v21, v22, v23
	v_cvt_pk_bf16_f32 v22, v16, v17
	v_cvt_pk_bf16_f32 v23, v18, v19
	global_store_dwordx4 v180, v[20:23], s[98:99] offset:256
	s_cbranch_execz .Ldry_epicf_real
.Ldry_epicf_c7:
	s_waitcnt vmcnt(15)
	v_lshlrev_b32_e32 v176, 16, v218
	v_and_b32_e32 v177, s19, v218
	v_lshlrev_b32_e32 v178, 16, v219
	v_and_b32_e32 v179, s19, v219
	v_lshlrev_b32_e32 v182, 16, v220
	v_and_b32_e32 v183, s19, v220
	v_lshlrev_b32_e32 v184, 16, v221
	v_and_b32_e32 v185, s19, v221
	v_pk_mul_f32 v[12:13], v[12:13], v[176:177]
	v_pk_mul_f32 v[14:15], v[14:15], v[178:179]
	v_pk_mul_f32 v[8:9], v[8:9], v[182:183]
	v_pk_mul_f32 v[10:11], v[10:11], v[184:185]
	v_cvt_pk_bf16_f32 v12, v12, v13
	v_cvt_pk_bf16_f32 v13, v14, v15
	v_cvt_pk_bf16_f32 v14, v8, v9
	v_cvt_pk_bf16_f32 v15, v10, v11
	v_add_u32_e32 v180, 0x58000, v181
	global_store_dwordx4 v180, v[12:15], s[98:99]
	s_waitcnt vmcnt(15)
	v_lshlrev_b32_e32 v176, 16, v222
	v_and_b32_e32 v177, s19, v222
	v_lshlrev_b32_e32 v178, 16, v223
	v_and_b32_e32 v179, s19, v223
	v_lshlrev_b32_e32 v182, 16, v224
	v_and_b32_e32 v183, s19, v224
	v_lshlrev_b32_e32 v184, 16, v225
	v_and_b32_e32 v185, s19, v225
	v_pk_mul_f32 v[4:5], v[4:5], v[176:177]
	v_pk_mul_f32 v[6:7], v[6:7], v[178:179]
	v_pk_mul_f32 v[0:1], v[0:1], v[182:183]
	v_pk_mul_f32 v[2:3], v[2:3], v[184:185]
	v_cvt_pk_bf16_f32 v4, v4, v5
	v_cvt_pk_bf16_f32 v5, v6, v7
	v_cvt_pk_bf16_f32 v6, v0, v1
	v_cvt_pk_bf16_f32 v7, v2, v3
	global_store_dwordx4 v180, v[4:7], s[98:99] offset:256
	s_cbranch_execz .Ldry_epicf_real
	s_branch .Lepic_done

; __device__ __forceinline__ float bf2f(unsigned u) { return __uint_as_float(u << 16); }
;     __device__ __forceinline__ void operator()(const f32x4 (&acc)[2][2][4][2], const pg8::Unit& u, int wr, int wc, int fr, int fq) const {
;     ...
;             u32x4 gv[2][2], tv[2][2];
; #pragma unroll
;             for (int mm = 0; mm < 2; ++mm)
; #pragma unroll
;                 for (int bj = 0; bj < 2; ++bj) {
;                     const size_t row = (size_t)(row0 + ai * 128 + (2 * mh + mm) * 16); const int col = col0 + bj * 128;
;                     gv[mm][bj] = *(const u32x4*)(gates + row * 2048 + (second ? 1024 : 0) + col);
;                     if (second) tv[mm][bj] = *(const u32x4*)((const bf16_t*)tmp + row * 1024 + col);
;                 }
; #pragma unroll
;             for (int mm = 0; mm < 2; ++mm)
; #pragma unroll
;                 for (int bj = 0; bj < 2; ++bj) {
;                     const int m = 2 * mh + mm;
;                     const size_t row = (size_t)(row0 + ai * 128 + m * 16); const int col = col0 + bj * 128;
;                     const u32x4 gt = gv[mm][bj];
;                     f32x4 a = acc[ai][bj][m][0], b = acc[ai][bj][m][1];
;                     a[0] *= bf2f(gt.x & 0xffffu); a[1] *= bf2f(gt.x >> 16); a[2] *= bf2f(gt.y & 0xffffu); a[3] *= bf2f(gt.y >> 16);
;                     b[0] *= bf2f(gt.z & 0xffffu); b[1] *= bf2f(gt.z >> 16); b[2] *= bf2f(gt.w & 0xffffu); b[3] *= bf2f(gt.w >> 16);
.Ldry_epics_real:
	s_mov_b64 exec, -1
	s_waitcnt vmcnt(15)
	v_lshlrev_b32_e32 v176, 16, v72
	v_and_b32_e32 v177, s19, v72
	v_lshlrev_b32_e32 v178, 16, v73
	v_and_b32_e32 v179, s19, v73
	v_lshlrev_b32_e32 v182, 16, v74
	v_and_b32_e32 v183, s19, v74
	v_lshlrev_b32_e32 v184, 16, v75
	v_and_b32_e32 v185, s19, v75
	v_pk_mul_f32 v[140:141], v[140:141], v[176:177]
	v_pk_mul_f32 v[142:143], v[142:143], v[178:179]
	v_pk_mul_f32 v[136:137], v[136:137], v[182:183]
	v_pk_mul_f32 v[138:139], v[138:139], v[184:185]
	v_mov_b32_e32 v180, v181
	global_load_dwordx4 v[72:75], v180, s[98:99]
	s_waitcnt vmcnt(15)
	v_lshlrev_b32_e32 v176, 16, v84
	v_and_b32_e32 v177, s19, v84
	v_lshlrev_b32_e32 v178, 16, v85
	v_and_b32_e32 v179, s19, v85
	v_lshlrev_b32_e32 v182, 16, v86
	v_and_b32_e32 v183, s19, v86
	v_lshlrev_b32_e32 v184, 16, v87
	v_and_b32_e32 v185, s19, v87
	v_pk_mul_f32 v[132:133], v[132:133], v[176:177]
	v_pk_mul_f32 v[134:135], v[134:135], v[178:179]
	v_pk_mul_f32 v[128:129], v[128:129], v[182:183]
	v_pk_mul_f32 v[130:131], v[130:131], v[184:185]
	global_load_dwordx4 v[84:87], v180, s[98:99] offset:256
	s_waitcnt vmcnt(15)
	v_lshlrev_b32_e32 v176, 16, v96
	v_and_b32_e32 v177, s19, v96
	v_lshlrev_b32_e32 v178, 16, v97
	v_and_b32_e32 v179, s19, v97
	v_lshlrev_b32_e32 v182, 16, v98
	v_and_b32_e32 v183, s19, v98
	v_lshlrev_b32_e32 v184, 16, v99
	v_and_b32_e32 v185, s19, v99
	v_pk_mul_f32 v[124:125], v[124:125], v[176:177]
	v_pk_mul_f32 v[126:127], v[126:127], v[178:179]
	v_pk_mul_f32 v[120:121], v[120:121], v[182:183]
	v_pk_mul_f32 v[122:123], v[122:123], v[184:185]
	v_add_u32_e32 v180, 0x8000, v181
	global_load_dwordx4 v[96:99], v180, s[98:99]
	s_waitcnt vmcnt(15)
	v_lshlrev_b32_e32 v176, 16, v100
	v_and_b32_e32 v177, s19, v100
	v_lshlrev_b32_e32 v178, 16, v101
	v_and_b32_e32 v179, s19, v101
	v_lshlrev_b32_e32 v182, 16, v102
	v_and_b32_e32 v183, s19, v102
	v_lshlrev_b32_e32 v184, 16, v103
	v_and_b32_e32 v185, s19, v103
	v_pk_mul_f32 v[116:117], v[116:117], v[176:177]
	v_pk_mul_f32 v[118:119], v[118:119], v[178:179]
	v_pk_mul_f32 v[112:113], v[112:113], v[182:183]
	v_pk_mul_f32 v[114:115], v[114:115], v[184:185]
	global_load_dwordx4 v[100:103], v180, s[98:99] offset:256
	s_waitcnt vmcnt(15)
	v_lshlrev_b32_e32 v176, 16, v144
	v_and_b32_e32 v177, s19, v144
	v_lshlrev_b32_e32 v178, 16, v145
	v_and_b32_e32 v179, s19, v145
	v_lshlrev_b32_e32 v182, 16, v146
	v_and_b32_e32 v183, s19, v146
	v_lshlrev_b32_e32 v184, 16, v147
	s_cbranch_execz .Ldry_epics_real
.Ldry_epics_c1:
	v_and_b32_e32 v185, s19, v147
	v_pk_mul_f32 v[108:109], v[108:109], v[176:177]
	v_pk_mul_f32 v[110:111], v[110:111], v[178:179]
	v_pk_mul_f32 v[104:105], v[104:105], v[182:183]
	v_pk_mul_f32 v[106:107], v[106:107], v[184:185]
	v_add_u32_e32 v180, 0x10000, v181
	global_load_dwordx4 v[144:147], v180, s[98:99]
	s_waitcnt vmcnt(15)
	v_lshlrev_b32_e32 v176, 16, v148
	v_and_b32_e32 v177, s19, v148
	v_lshlrev_b32_e32 v178, 16, v149
	v_and_b32_e32 v179, s19, v149
	v_lshlrev_b32_e32 v182, 16, v150
	v_and_b32_e32 v183, s19, v150
	v_lshlrev_b32_e32 v184, 16, v151
	v_and_b32_e32 v185, s19, v151
	v_pk_mul_f32 v[92:93], v[92:93], v[176:177]
	v_pk_mul_f32 v[94:95], v[94:95], v[178:179]
	v_pk_mul_f32 v[88:89], v[88:89], v[182:183]
	v_pk_mul_f32 v[90:91], v[90:91], v[184:185]
	global_load_dwordx4 v[148:151], v180, s[98:99] offset:256
	s_waitcnt vmcnt(15)
	v_lshlrev_b32_e32 v176, 16, v152
	v_and_b32_e32 v177, s19, v152
	v_lshlrev_b32_e32 v178, 16, v153
	v_and_b32_e32 v179, s19, v153
	v_lshlrev_b32_e32 v182, 16, v154
	v_and_b32_e32 v183, s19, v154
	v_lshlrev_b32_e32 v184, 16, v155
	v_and_b32_e32 v185, s19, v155
	v_pk_mul_f32 v[80:81], v[80:81], v[176:177]
	v_pk_mul_f32 v[82:83], v[82:83], v[178:179]
	v_pk_mul_f32 v[76:77], v[76:77], v[182:183]
	v_pk_mul_f32 v[78:79], v[78:79], v[184:185]
	v_add_u32_e32 v180, 0x18000, v181
	global_load_dwordx4 v[152:155], v180, s[98:99]
	s_waitcnt vmcnt(15)
	v_lshlrev_b32_e32 v176, 16, v156
	v_and_b32_e32 v177, s19, v156
	v_lshlrev_b32_e32 v178, 16, v157
	v_and_b32_e32 v179, s19, v157
	v_lshlrev_b32_e32 v182, 16, v158
	v_and_b32_e32 v183, s19, v158
	v_lshlrev_b32_e32 v184, 16, v159
	v_and_b32_e32 v185, s19, v159
	v_pk_mul_f32 v[68:69], v[68:69], v[176:177]
	v_pk_mul_f32 v[70:71], v[70:71], v[178:179]
	v_pk_mul_f32 v[64:65], v[64:65], v[182:183]
	v_pk_mul_f32 v[66:67], v[66:67], v[184:185]
	global_load_dwordx4 v[156:159], v180, s[98:99] offset:256
	s_waitcnt vmcnt(15)
	v_lshlrev_b32_e32 v176, 16, v192
	v_and_b32_e32 v177, s19, v192
	v_lshlrev_b32_e32 v178, 16, v193
	v_and_b32_e32 v179, s19, v193
	v_lshlrev_b32_e32 v182, 16, v194
	v_and_b32_e32 v183, s19, v194
	v_lshlrev_b32_e32 v184, 16, v195
	v_and_b32_e32 v185, s19, v195
	v_pk_mul_f32 v[60:61], v[60:61], v[176:177]
	v_pk_mul_f32 v[62:63], v[62:63], v[178:179]
	v_pk_mul_f32 v[56:57], v[56:57], v[182:183]
	v_pk_mul_f32 v[58:59], v[58:59], v[184:185]
	v_add_u32_e32 v180, 0x40000, v181
	global_load_dwordx4 v[192:195], v180, s[98:99]
	s_waitcnt vmcnt(15)
	s_cbranch_execz .Ldry_epics_real
; __device__ __forceinline__ unsigned cvt_pk_bf16(float lo, float hi) { f32x2_t v = {lo, hi}; bf16x2_t b = __builtin_convertvector(v, bf16x2_t); return __builtin_bit_cast(unsigned, b); }
; __device__ __forceinline__ float bf2f(unsigned u) { return __uint_as_float(u << 16); }
;     __device__ __forceinline__ void operator()(const f32x4 (&acc)[2][2][4][2], const pg8::Unit& u, int wr, int wc, int fr, int fq) const {
;     ...
;                     const u32x4 gt = gv[mm][bj];
;                     f32x4 a = acc[ai][bj][m][0], b = acc[ai][bj][m][1];
;                     a[0] *= bf2f(gt.x & 0xffffu); a[1] *= bf2f(gt.x >> 16); a[2] *= bf2f(gt.y & 0xffffu); a[3] *= bf2f(gt.y >> 16);
;                     b[0] *= bf2f(gt.z & 0xffffu); b[1] *= bf2f(gt.z >> 16); b[2] *= bf2f(gt.w & 0xffffu); b[3] *= bf2f(gt.w >> 16);
;                     if (!second) { u32x4 w; w.x = cvt_pk_bf16(a[0], a[1]); w.y = cvt_pk_bf16(a[2], a[3]); w.z = cvt_pk_bf16(b[0], b[1]); w.w = cvt_pk_bf16(b[2], b[3]); *(u32x4*)((bf16_t*)tmp + row * 1024 + col) = w; }
;                     else {
;                         { const u32x4 t = tv[mm][bj]; a[0] += bf2f(t.x & 0xffffu); a[1] += bf2f(t.x >> 16); a[2] += bf2f(t.y & 0xffffu); a[3] += bf2f(t.y >> 16);
;                           b[0] += bf2f(t.z & 0xffffu); b[1] += bf2f(t.z >> 16); b[2] += bf2f(t.w & 0xffffu); b[3] += bf2f(t.w >> 16); }
;                         u32x4 w; w.x = cvt_pk_bf16(a[0], a[1]); w.y = cvt_pk_bf16(a[2], a[3]); w.z = cvt_pk_bf16(b[0], b[1]); w.w = cvt_pk_bf16(b[2], b[3]);
;                         *(u32x4*)(Y + row * 1024 + col) = w;
.Ldry_epics_c2:
	v_lshlrev_b32_e32 v176, 16, v196
	v_and_b32_e32 v177, s19, v196
	v_lshlrev_b32_e32 v178, 16, v197
	v_and_b32_e32 v179, s19, v197
	v_lshlrev_b32_e32 v182, 16, v198
	v_and_b32_e32 v183, s19, v198
	v_lshlrev_b32_e32 v184, 16, v199
	v_and_b32_e32 v185, s19, v199
	v_pk_mul_f32 v[52:53], v[52:53], v[176:177]
	v_pk_mul_f32 v[54:55], v[54:55], v[178:179]
	v_pk_mul_f32 v[48:49], v[48:49], v[182:183]
	v_pk_mul_f32 v[50:51], v[50:51], v[184:185]
	global_load_dwordx4 v[196:199], v180, s[98:99] offset:256
	s_waitcnt vmcnt(15)
	v_lshlrev_b32_e32 v176, 16, v202
	v_and_b32_e32 v177, s19, v202
	v_lshlrev_b32_e32 v178, 16, v203
	v_and_b32_e32 v179, s19, v203
	v_lshlrev_b32_e32 v182, 16, v204
	v_and_b32_e32 v183, s19, v204
	v_lshlrev_b32_e32 v184, 16, v205
	v_and_b32_e32 v185, s19, v205
	v_pk_mul_f32 v[44:45], v[44:45], v[176:177]
	v_pk_mul_f32 v[46:47], v[46:47], v[178:179]
	v_pk_mul_f32 v[40:41], v[40:41], v[182:183]
	v_pk_mul_f32 v[42:43], v[42:43], v[184:185]
	v_add_u32_e32 v180, 0x48000, v181
	global_load_dwordx4 v[202:205], v180, s[98:99]
	s_waitcnt vmcnt(15)
	v_lshlrev_b32_e32 v176, 16, v206
	v_and_b32_e32 v177, s19, v206
	v_lshlrev_b32_e32 v178, 16, v207
	v_and_b32_e32 v179, s19, v207
	v_lshlrev_b32_e32 v182, 16, v208
	v_and_b32_e32 v183, s19, v208
	v_lshlrev_b32_e32 v184, 16, v209
	v_and_b32_e32 v185, s19, v209
	v_pk_mul_f32 v[36:37], v[36:37], v[176:177]
	v_pk_mul_f32 v[38:39], v[38:39], v[178:179]
	v_pk_mul_f32 v[32:33], v[32:33], v[182:183]
	v_pk_mul_f32 v[34:35], v[34:35], v[184:185]
	global_load_dwordx4 v[206:209], v180, s[98:99] offset:256
	s_waitcnt vmcnt(15)
	v_lshlrev_b32_e32 v176, 16, v210
	v_and_b32_e32 v177, s19, v210
	v_lshlrev_b32_e32 v178, 16, v211
	v_and_b32_e32 v179, s19, v211
	v_lshlrev_b32_e32 v182, 16, v212
	v_and_b32_e32 v183, s19, v212
	v_lshlrev_b32_e32 v184, 16, v213
	v_and_b32_e32 v185, s19, v213
	v_pk_mul_f32 v[28:29], v[28:29], v[176:177]
	v_pk_mul_f32 v[30:31], v[30:31], v[178:179]
	v_pk_mul_f32 v[24:25], v[24:25], v[182:183]
	v_pk_mul_f32 v[26:27], v[26:27], v[184:185]
	v_add_u32_e32 v180, 0x50000, v181
	global_load_dwordx4 v[210:213], v180, s[98:99]
	s_waitcnt vmcnt(15)
	v_lshlrev_b32_e32 v176, 16, v214
	v_and_b32_e32 v177, s19, v214
	v_lshlrev_b32_e32 v178, 16, v215
	v_and_b32_e32 v179, s19, v215
	v_lshlrev_b32_e32 v182, 16, v216
	v_and_b32_e32 v183, s19, v216
	v_lshlrev_b32_e32 v184, 16, v217
	v_and_b32_e32 v185, s19, v217
	s_cbranch_execz .Ldry_epics_real
.Ldry_epics_c3:
	v_pk_mul_f32 v[20:21], v[20:21], v[176:177]
	v_pk_mul_f32 v[22:23], v[22:23], v[178:179]
	v_pk_mul_f32 v[16:17], v[16:17], v[182:183]
	v_pk_mul_f32 v[18:19], v[18:19], v[184:185]
	global_load_dwordx4 v[214:217], v180, s[98:99] offset:256
	s_waitcnt vmcnt(15)
	v_lshlrev_b32_e32 v176, 16, v218
	v_and_b32_e32 v177, s19, v218
	v_lshlrev_b32_e32 v178, 16, v219
	v_and_b32_e32 v179, s19, v219
	v_lshlrev_b32_e32 v182, 16, v220
	v_and_b32_e32 v183, s19, v220
	v_lshlrev_b32_e32 v184, 16, v221
	v_and_b32_e32 v185, s19, v221
	v_pk_mul_f32 v[12:13], v[12:13], v[176:177]
	v_pk_mul_f32 v[14:15], v[14:15], v[178:179]
	v_pk_mul_f32 v[8:9], v[8:9], v[182:183]
	v_pk_mul_f32 v[10:11], v[10:11], v[184:185]
	v_add_u32_e32 v180, 0x58000, v181
	global_load_dwordx4 v[218:221], v180, s[98:99]
	s_waitcnt vmcnt(15)
	v_lshlrev_b32_e32 v176, 16, v222
	v_and_b32_e32 v177, s19, v222
	v_lshlrev_b32_e32 v178, 16, v223
	v_and_b32_e32 v179, s19, v223
	v_lshlrev_b32_e32 v182, 16, v224
	v_and_b32_e32 v183, s19, v224
	v_lshlrev_b32_e32 v184, 16, v225
	v_and_b32_e32 v185, s19, v225
	v_pk_mul_f32 v[4:5], v[4:5], v[176:177]
	v_pk_mul_f32 v[6:7], v[6:7], v[178:179]
	v_pk_mul_f32 v[0:1], v[0:1], v[182:183]
	v_pk_mul_f32 v[2:3], v[2:3], v[184:185]
	global_load_dwordx4 v[222:225], v180, s[98:99] offset:256
	s_waitcnt vmcnt(15)
	v_lshlrev_b32_e32 v176, 16, v72
	v_and_b32_e32 v177, s19, v72
	v_lshlrev_b32_e32 v178, 16, v73
	v_and_b32_e32 v179, s19, v73
	v_lshlrev_b32_e32 v182, 16, v74
	v_and_b32_e32 v183, s19, v74
	v_lshlrev_b32_e32 v184, 16, v75
	v_and_b32_e32 v185, s19, v75
	v_pk_add_f32 v[140:141], v[140:141], v[176:177]
	v_pk_add_f32 v[142:143], v[142:143], v[178:179]
	v_pk_add_f32 v[136:137], v[136:137], v[182:183]
	v_pk_add_f32 v[138:139], v[138:139], v[184:185]
	v_cvt_pk_bf16_f32 v140, v140, v141
	v_cvt_pk_bf16_f32 v141, v142, v143
	v_cvt_pk_bf16_f32 v142, v136, v137
	v_cvt_pk_bf16_f32 v143, v138, v139
	v_mov_b32_e32 v180, v181
	global_store_dwordx4 v180, v[140:143], s[42:43]
	s_waitcnt vmcnt(15)
	v_lshlrev_b32_e32 v176, 16, v84
	v_and_b32_e32 v177, s19, v84
	v_lshlrev_b32_e32 v178, 16, v85
	v_and_b32_e32 v179, s19, v85
	v_lshlrev_b32_e32 v182, 16, v86
	v_and_b32_e32 v183, s19, v86
	v_lshlrev_b32_e32 v184, 16, v87
	v_and_b32_e32 v185, s19, v87
	v_pk_add_f32 v[132:133], v[132:133], v[176:177]
	v_pk_add_f32 v[134:135], v[134:135], v[178:179]
	v_pk_add_f32 v[128:129], v[128:129], v[182:183]
	v_pk_add_f32 v[130:131], v[130:131], v[184:185]
	s_cbranch_execz .Ldry_epics_real
